# prep_w (next layer FFN1 gate/up/down): 16 tile loads (+16 gain loads) issued together with counted waits instead of one round trip per element
# speedup vs baseline: 1.0112x; 1.0041x over previous
; DI void prep_w(int vb, int nvb, const float* __restrict__ W, bf16_t* __restrict__ Wt, int K, int N, const float* __restrict__ gk, const float* __restrict__ sn, int mode, float* smf) {
;     ...
; #pragma unroll
;       for (int i = 0; i < 16; ++i) {
;         const int kk = i * 4 + (tid >> 6), nn = tid & 63;
;         float v = __builtin_nontemporal_load(W + (size_t)(k0 + kk) * N + n0 + nn);
;         if (gk) v *= gk[k0 + kk];
;         if (sn) v *= sn[n0 + nn];
;         smf[kk * 65 + nn] = v;
;       }
.LBB0_625:
	s_add_i32 s3, s95, s2
	s_cmpk_lt_i32 s3, 0x2c0
	s_mul_hi_i32 s10, s3, 0x2e8ba2e9
	s_cselect_b64 s[38:39], -1, 0
	s_lshr_b32 s11, s10, 31
	s_ashr_i32 s10, s10, 3
	s_add_i32 s11, s10, s11
	s_lshl_b32 s10, s11, 6
	s_mul_i32 s11, s11, 44
	s_sub_i32 s11, s3, s11
	s_lshl_b32 s14, s11, 6
	s_cmpk_gt_i32 s3, 0x2bf
	s_cbranch_scc1 .LBB0_627
	s_ashr_i32 s15, s14, 31
	v_lshl_add_u64 v[4:5], s[14:15], 2, v[2:3]
	v_add_u32_e32 v6, s10, v10
	v_ashrrev_i32_e32 v7, 31, v6
	v_mad_i64_i32 v[8:9], s[54:55], v6, s73, v[4:5]
	global_load_dword v35, v[8:9], off nt
	v_lshl_add_u64 v[8:9], v[6:7], 2, s[8:9]
	global_load_dword v36, v[8:9], off
	v_add_u32_e32 v7, 4, v6
	v_mad_i64_i32 v[30:31], s[54:55], v7, s73, v[4:5]
	global_load_dword v37, v[30:31], off nt
	global_load_dword v38, v[8:9], off offset:16
	v_add_u32_e32 v7, 8, v6
	v_mad_i64_i32 v[30:31], s[54:55], v7, s73, v[4:5]
	global_load_dword v39, v[30:31], off nt
	global_load_dword v40, v[8:9], off offset:32
	v_add_u32_e32 v7, 12, v6
	v_mad_i64_i32 v[30:31], s[54:55], v7, s73, v[4:5]
	global_load_dword v41, v[30:31], off nt
	global_load_dword v42, v[8:9], off offset:48
	v_add_u32_e32 v7, 16, v6
	v_mad_i64_i32 v[30:31], s[54:55], v7, s73, v[4:5]
	global_load_dword v43, v[30:31], off nt
	global_load_dword v44, v[8:9], off offset:64
	v_add_u32_e32 v7, 20, v6
	v_mad_i64_i32 v[30:31], s[54:55], v7, s73, v[4:5]
	global_load_dword v45, v[30:31], off nt
	global_load_dword v46, v[8:9], off offset:80
	v_add_u32_e32 v7, 24, v6
	v_mad_i64_i32 v[30:31], s[54:55], v7, s73, v[4:5]
	global_load_dword v47, v[30:31], off nt
	global_load_dword v48, v[8:9], off offset:96
	v_add_u32_e32 v7, 28, v6
	v_mad_i64_i32 v[30:31], s[54:55], v7, s73, v[4:5]
	global_load_dword v49, v[30:31], off nt
	global_load_dword v50, v[8:9], off offset:112
	v_add_u32_e32 v7, 32, v6
	v_mad_i64_i32 v[30:31], s[54:55], v7, s73, v[4:5]
	global_load_dword v51, v[30:31], off nt
	global_load_dword v52, v[8:9], off offset:128
	v_add_u32_e32 v7, 36, v6
	v_mad_i64_i32 v[30:31], s[54:55], v7, s73, v[4:5]
	global_load_dword v53, v[30:31], off nt
	global_load_dword v54, v[8:9], off offset:144
	v_add_u32_e32 v7, 40, v6
	v_mad_i64_i32 v[30:31], s[54:55], v7, s73, v[4:5]
	global_load_dword v55, v[30:31], off nt
	global_load_dword v56, v[8:9], off offset:160
	v_add_u32_e32 v7, 44, v6
	v_mad_i64_i32 v[30:31], s[54:55], v7, s73, v[4:5]
	global_load_dword v57, v[30:31], off nt
	global_load_dword v58, v[8:9], off offset:176
	v_add_u32_e32 v7, 48, v6
	v_mad_i64_i32 v[30:31], s[54:55], v7, s73, v[4:5]
	global_load_dword v59, v[30:31], off nt
	global_load_dword v60, v[8:9], off offset:192
	v_add_u32_e32 v7, 52, v6
	v_mad_i64_i32 v[30:31], s[54:55], v7, s73, v[4:5]
	global_load_dword v61, v[30:31], off nt
	global_load_dword v62, v[8:9], off offset:208
	v_add_u32_e32 v7, 56, v6
	v_mad_i64_i32 v[30:31], s[54:55], v7, s73, v[4:5]
	global_load_dword v63, v[30:31], off nt
	global_load_dword v64, v[8:9], off offset:224
	v_add_u32_e32 v6, 60, v6
	v_mad_i64_i32 v[4:5], s[54:55], v6, s73, v[4:5]
	global_load_dword v65, v[4:5], off nt
	global_load_dword v66, v[8:9], off offset:240
	s_waitcnt vmcnt(30)
	v_mul_f32_e32 v7, v35, v36
	ds_write_b32 v14, v7
	s_waitcnt vmcnt(28)
	v_mul_f32_e32 v7, v37, v38
	ds_write_b32 v15, v7
	s_waitcnt vmcnt(26)
	v_mul_f32_e32 v7, v39, v40
	ds_write_b32 v16, v7
	s_waitcnt vmcnt(24)
	v_mul_f32_e32 v7, v41, v42
	ds_write_b32 v17, v7
	s_waitcnt vmcnt(22)
	v_mul_f32_e32 v7, v43, v44
	ds_write_b32 v18, v7
	s_waitcnt vmcnt(20)
	v_mul_f32_e32 v7, v45, v46
	ds_write_b32 v19, v7
	s_waitcnt vmcnt(18)
	v_mul_f32_e32 v7, v47, v48
	ds_write_b32 v20, v7
	s_waitcnt vmcnt(16)
	v_mul_f32_e32 v7, v49, v50
	ds_write_b32 v21, v7
	s_waitcnt vmcnt(14)
	v_mul_f32_e32 v7, v51, v52
	ds_write_b32 v22, v7
	s_waitcnt vmcnt(12)
	v_mul_f32_e32 v7, v53, v54
	ds_write_b32 v23, v7
	s_waitcnt vmcnt(10)
	v_mul_f32_e32 v7, v55, v56
	ds_write_b32 v24, v7
	s_waitcnt vmcnt(8)
	v_mul_f32_e32 v7, v57, v58
	ds_write_b32 v25, v7
	s_waitcnt vmcnt(6)
	v_mul_f32_e32 v7, v59, v60
	ds_write_b32 v26, v7
	s_waitcnt vmcnt(4)
	v_mul_f32_e32 v7, v61, v62
	ds_write_b32 v27, v7
	s_waitcnt vmcnt(2)
	v_mul_f32_e32 v7, v63, v64
	ds_write_b32 v28, v7
	s_waitcnt vmcnt(0)
	v_mul_f32_e32 v4, v65, v66
	ds_write_b32 v29, v4

; DI void prep_w(int vb, int nvb, const float* __restrict__ W, bf16_t* __restrict__ Wt, int K, int N, const float* __restrict__ gk, const float* __restrict__ sn, int mode, float* smf) {
;     ...
; #pragma unroll
;       for (int i = 0; i < 16; ++i) {
;         const int kk = i * 4 + (tid >> 6), nn = tid & 63;
;         float v = __builtin_nontemporal_load(W + (size_t)(k0 + kk) * N + n0 + nn);
;         if (gk) v *= gk[k0 + kk];
;         if (sn) v *= sn[n0 + nn];
;         smf[kk * 65 + nn] = v;
;       }
.LBB0_631:
	s_add_i32 s3, s95, s2
	s_cmpk_lt_i32 s3, 0x2c0
	s_mul_hi_i32 s10, s3, 0x2e8ba2e9
	s_cselect_b64 s[38:39], -1, 0
	s_lshr_b32 s11, s10, 31
	s_ashr_i32 s10, s10, 3
	s_add_i32 s11, s10, s11
	s_lshl_b32 s10, s11, 6
	s_mul_i32 s11, s11, 44
	s_sub_i32 s11, s3, s11
	s_lshl_b32 s14, s11, 6
	s_cmpk_gt_i32 s3, 0x2bf
	s_cbranch_scc1 .LBB0_633
	s_ashr_i32 s15, s14, 31
	v_lshl_add_u64 v[4:5], s[14:15], 2, v[2:3]
	v_add_u32_e32 v6, s10, v10
	v_ashrrev_i32_e32 v7, 31, v6
	v_mad_i64_i32 v[8:9], s[54:55], v6, s73, v[4:5]
	global_load_dword v35, v[8:9], off nt
	v_lshl_add_u64 v[8:9], v[6:7], 2, s[8:9]
	global_load_dword v36, v[8:9], off
	v_add_u32_e32 v7, 4, v6
	v_mad_i64_i32 v[30:31], s[54:55], v7, s73, v[4:5]
	global_load_dword v37, v[30:31], off nt
	global_load_dword v38, v[8:9], off offset:16
	v_add_u32_e32 v7, 8, v6
	v_mad_i64_i32 v[30:31], s[54:55], v7, s73, v[4:5]
	global_load_dword v39, v[30:31], off nt
	global_load_dword v40, v[8:9], off offset:32
	v_add_u32_e32 v7, 12, v6
	v_mad_i64_i32 v[30:31], s[54:55], v7, s73, v[4:5]
	global_load_dword v41, v[30:31], off nt
	global_load_dword v42, v[8:9], off offset:48
	v_add_u32_e32 v7, 16, v6
	v_mad_i64_i32 v[30:31], s[54:55], v7, s73, v[4:5]
	global_load_dword v43, v[30:31], off nt
	global_load_dword v44, v[8:9], off offset:64
	v_add_u32_e32 v7, 20, v6
	v_mad_i64_i32 v[30:31], s[54:55], v7, s73, v[4:5]
	global_load_dword v45, v[30:31], off nt
	global_load_dword v46, v[8:9], off offset:80
	v_add_u32_e32 v7, 24, v6
	v_mad_i64_i32 v[30:31], s[54:55], v7, s73, v[4:5]
	global_load_dword v47, v[30:31], off nt
	global_load_dword v48, v[8:9], off offset:96
	v_add_u32_e32 v7, 28, v6
	v_mad_i64_i32 v[30:31], s[54:55], v7, s73, v[4:5]
	global_load_dword v49, v[30:31], off nt
	global_load_dword v50, v[8:9], off offset:112
	v_add_u32_e32 v7, 32, v6
	v_mad_i64_i32 v[30:31], s[54:55], v7, s73, v[4:5]
	global_load_dword v51, v[30:31], off nt
	global_load_dword v52, v[8:9], off offset:128
	v_add_u32_e32 v7, 36, v6
	v_mad_i64_i32 v[30:31], s[54:55], v7, s73, v[4:5]
	global_load_dword v53, v[30:31], off nt
	global_load_dword v54, v[8:9], off offset:144
	v_add_u32_e32 v7, 40, v6
	v_mad_i64_i32 v[30:31], s[54:55], v7, s73, v[4:5]
	global_load_dword v55, v[30:31], off nt
	global_load_dword v56, v[8:9], off offset:160
	v_add_u32_e32 v7, 44, v6
	v_mad_i64_i32 v[30:31], s[54:55], v7, s73, v[4:5]
	global_load_dword v57, v[30:31], off nt
	global_load_dword v58, v[8:9], off offset:176
	v_add_u32_e32 v7, 48, v6
	v_mad_i64_i32 v[30:31], s[54:55], v7, s73, v[4:5]
	global_load_dword v59, v[30:31], off nt
	global_load_dword v60, v[8:9], off offset:192
	v_add_u32_e32 v7, 52, v6
	v_mad_i64_i32 v[30:31], s[54:55], v7, s73, v[4:5]
	global_load_dword v61, v[30:31], off nt
	global_load_dword v62, v[8:9], off offset:208
	v_add_u32_e32 v7, 56, v6
	v_mad_i64_i32 v[30:31], s[54:55], v7, s73, v[4:5]
	global_load_dword v63, v[30:31], off nt
	global_load_dword v64, v[8:9], off offset:224
	v_add_u32_e32 v6, 60, v6
	v_mad_i64_i32 v[4:5], s[54:55], v6, s73, v[4:5]
	global_load_dword v65, v[4:5], off nt
	global_load_dword v66, v[8:9], off offset:240
	s_waitcnt vmcnt(30)
	v_mul_f32_e32 v7, v35, v36
	ds_write_b32 v13, v7
	s_waitcnt vmcnt(28)
	v_mul_f32_e32 v7, v37, v38
	ds_write_b32 v14, v7
	s_waitcnt vmcnt(26)
	v_mul_f32_e32 v7, v39, v40
	ds_write_b32 v15, v7
	s_waitcnt vmcnt(24)
	v_mul_f32_e32 v7, v41, v42
	ds_write_b32 v16, v7
	s_waitcnt vmcnt(22)
	v_mul_f32_e32 v7, v43, v44
	ds_write_b32 v17, v7
	s_waitcnt vmcnt(20)
	v_mul_f32_e32 v7, v45, v46
	ds_write_b32 v18, v7
	s_waitcnt vmcnt(18)
	v_mul_f32_e32 v7, v47, v48
	ds_write_b32 v19, v7
	s_waitcnt vmcnt(16)
	v_mul_f32_e32 v7, v49, v50
	ds_write_b32 v20, v7
	s_waitcnt vmcnt(14)
	v_mul_f32_e32 v7, v51, v52
	ds_write_b32 v21, v7
	s_waitcnt vmcnt(12)
	v_mul_f32_e32 v7, v53, v54
	ds_write_b32 v22, v7
	s_waitcnt vmcnt(10)
	v_mul_f32_e32 v7, v55, v56
	ds_write_b32 v23, v7
	s_waitcnt vmcnt(8)
	v_mul_f32_e32 v7, v57, v58
	ds_write_b32 v24, v7
	s_waitcnt vmcnt(6)
	v_mul_f32_e32 v7, v59, v60
	ds_write_b32 v25, v7
	s_waitcnt vmcnt(4)
	v_mul_f32_e32 v7, v61, v62
	ds_write_b32 v26, v7
	s_waitcnt vmcnt(2)
	v_mul_f32_e32 v7, v63, v64
	ds_write_b32 v27, v7
	s_waitcnt vmcnt(0)
	v_mul_f32_e32 v4, v65, v66
	ds_write_b32 v28, v4

; DI void prep_w(int vb, int nvb, const float* __restrict__ W, bf16_t* __restrict__ Wt, int K, int N, const float* __restrict__ gk, const float* __restrict__ sn, int mode, float* smf) {
;     ...
; #pragma unroll
;       for (int i = 0; i < 16; ++i) {
;         const int kk = i * 4 + (tid >> 6), nn = tid & 63;
;         float v = __builtin_nontemporal_load(W + (size_t)(k0 + kk) * N + n0 + nn);
;         if (gk) v *= gk[k0 + kk];
;         if (sn) v *= sn[n0 + nn];
;         smf[kk * 65 + nn] = v;
.LBB0_637:
	s_add_i32 s1, s95, s2
	s_cmpk_lt_i32 s1, 0x2c0
	s_cselect_b64 s[10:11], -1, 0
	s_ashr_i32 s0, s1, 31
	s_lshr_b32 s0, s0, 28
	s_add_i32 s3, s1, s0
	s_lshl_b32 s0, s3, 2
	s_and_b32 s3, s3, 0x3fffff0
	s_sub_i32 s3, s1, s3
	s_andn2_b32 s0, s0, 63
	s_lshl_b32 s8, s3, 6
	s_cmpk_gt_i32 s1, 0x2bf
	s_cbranch_scc1 .LBB0_639
	v_add_u32_e32 v26, s0, v4
	s_ashr_i32 s9, s8, 31
	v_ashrrev_i32_e32 v27, 31, v26
	v_lshl_add_u64 v[24:25], s[8:9], 2, v[2:3]
	v_lshlrev_b64 v[28:29], 12, v[26:27]
	v_lshl_add_u64 v[28:29], v[24:25], 0, v[28:29]
	global_load_dword v34, v[28:29], off nt
	v_add_u32_e32 v28, 4, v26
	v_ashrrev_i32_e32 v29, 31, v28
	v_lshlrev_b64 v[28:29], 12, v[28:29]
	v_lshl_add_u64 v[28:29], v[24:25], 0, v[28:29]
	global_load_dword v35, v[28:29], off nt
	v_add_u32_e32 v28, 8, v26
	v_ashrrev_i32_e32 v29, 31, v28
	v_lshlrev_b64 v[28:29], 12, v[28:29]
	v_lshl_add_u64 v[28:29], v[24:25], 0, v[28:29]
	global_load_dword v36, v[28:29], off nt
	v_add_u32_e32 v28, 12, v26
	v_ashrrev_i32_e32 v29, 31, v28
	v_lshlrev_b64 v[28:29], 12, v[28:29]
	v_lshl_add_u64 v[28:29], v[24:25], 0, v[28:29]
	global_load_dword v37, v[28:29], off nt
	v_add_u32_e32 v28, 16, v26
	v_ashrrev_i32_e32 v29, 31, v28
	v_lshlrev_b64 v[28:29], 12, v[28:29]
	v_lshl_add_u64 v[28:29], v[24:25], 0, v[28:29]
	global_load_dword v38, v[28:29], off nt
	v_add_u32_e32 v28, 20, v26
	v_ashrrev_i32_e32 v29, 31, v28
	v_lshlrev_b64 v[28:29], 12, v[28:29]
	v_lshl_add_u64 v[28:29], v[24:25], 0, v[28:29]
	global_load_dword v39, v[28:29], off nt
	v_add_u32_e32 v28, 24, v26
	v_ashrrev_i32_e32 v29, 31, v28
	v_lshlrev_b64 v[28:29], 12, v[28:29]
	v_lshl_add_u64 v[28:29], v[24:25], 0, v[28:29]
	global_load_dword v40, v[28:29], off nt
	v_add_u32_e32 v28, 28, v26
	v_ashrrev_i32_e32 v29, 31, v28
	v_lshlrev_b64 v[28:29], 12, v[28:29]
	v_lshl_add_u64 v[28:29], v[24:25], 0, v[28:29]
	global_load_dword v41, v[28:29], off nt
	v_add_u32_e32 v28, 32, v26
	v_ashrrev_i32_e32 v29, 31, v28
	v_lshlrev_b64 v[28:29], 12, v[28:29]
	v_lshl_add_u64 v[28:29], v[24:25], 0, v[28:29]
	global_load_dword v42, v[28:29], off nt
	v_add_u32_e32 v28, 36, v26
	v_ashrrev_i32_e32 v29, 31, v28
	v_lshlrev_b64 v[28:29], 12, v[28:29]
	v_lshl_add_u64 v[28:29], v[24:25], 0, v[28:29]
	global_load_dword v43, v[28:29], off nt
	v_add_u32_e32 v28, 40, v26
	v_ashrrev_i32_e32 v29, 31, v28
	v_lshlrev_b64 v[28:29], 12, v[28:29]
	v_lshl_add_u64 v[28:29], v[24:25], 0, v[28:29]
	global_load_dword v44, v[28:29], off nt
	v_add_u32_e32 v28, 44, v26
	v_ashrrev_i32_e32 v29, 31, v28
	v_lshlrev_b64 v[28:29], 12, v[28:29]
	v_lshl_add_u64 v[28:29], v[24:25], 0, v[28:29]
	global_load_dword v45, v[28:29], off nt
	v_add_u32_e32 v28, 48, v26
	v_ashrrev_i32_e32 v29, 31, v28
	v_lshlrev_b64 v[28:29], 12, v[28:29]
	v_lshl_add_u64 v[28:29], v[24:25], 0, v[28:29]
	global_load_dword v46, v[28:29], off nt
	v_add_u32_e32 v28, 52, v26
	v_ashrrev_i32_e32 v29, 31, v28
	v_lshlrev_b64 v[28:29], 12, v[28:29]
	v_lshl_add_u64 v[28:29], v[24:25], 0, v[28:29]
	global_load_dword v47, v[28:29], off nt
	v_add_u32_e32 v28, 56, v26
	v_ashrrev_i32_e32 v29, 31, v28
	v_lshlrev_b64 v[28:29], 12, v[28:29]
	v_lshl_add_u64 v[28:29], v[24:25], 0, v[28:29]
	v_add_u32_e32 v26, 60, v26
	v_ashrrev_i32_e32 v27, 31, v26
	v_lshlrev_b64 v[26:27], 12, v[26:27]
	v_lshl_add_u64 v[24:25], v[24:25], 0, v[26:27]
	global_load_dword v48, v[28:29], off nt
	global_load_dword v49, v[24:25], off nt
	s_waitcnt vmcnt(15)
	ds_write_b32 v7, v34
	s_waitcnt vmcnt(14)
	ds_write_b32 v8, v35
	s_waitcnt vmcnt(13)
	ds_write_b32 v9, v36
	s_waitcnt vmcnt(12)
	ds_write_b32 v10, v37
	s_waitcnt vmcnt(11)
	ds_write_b32 v11, v38
	s_waitcnt vmcnt(10)
	ds_write_b32 v12, v39
	s_waitcnt vmcnt(9)
	ds_write_b32 v13, v40
	s_waitcnt vmcnt(8)
	ds_write_b32 v14, v41
	s_waitcnt vmcnt(7)
	ds_write_b32 v15, v42
	s_waitcnt vmcnt(6)
	ds_write_b32 v16, v43
	s_waitcnt vmcnt(5)
	ds_write_b32 v17, v44
	s_waitcnt vmcnt(4)
	ds_write_b32 v18, v45
	s_waitcnt vmcnt(3)
	ds_write_b32 v19, v46
	s_waitcnt vmcnt(2)
	ds_write_b32 v20, v47
	s_waitcnt vmcnt(1)
	ds_write_b32 v21, v48
	s_waitcnt vmcnt(0)
	ds_write_b32 v22, v49
